# EpiF32 split-K partial stores write-through (sc1), row-exchange slot loads batched + redundant acquire-invalidate dropped (sc1 loads/stores), m1 state V loads hoisted next to K loads
# speedup vs baseline: 1.0204x; 1.0052x over previous
; __device__ __forceinline__ void m1_rope_states(const KQ p_in, int e, float* sm) {
;     ...
;         const int kc = 1792 + h * 64, vc = 2304 + h * 64;
;         {
;             const int r = tid >> 2, pq = tid & 3;
;             bf16_t* zp = Z + (size_t)(t0 + r) * INW + kc + 8 * pq;
;             const bf16x8 a1 = *(const bf16x8*)zp, a2 = *(const bf16x8*)(zp + 32);
;             float o1[8], o2[8];
;             if (lat) {
;                 const int pos = (t0 + r) & (SEQ - 1);
;                 const float* cp = rope + (size_t)2 * SEQ * 32 + pos * 32 + 8 * pq; const float* sp = cp + (size_t)SEQ * 32;
;                 const f32x4 c0 = *(const f32x4*)cp, c1 = *(const f32x4*)(cp + 4), s0 = *(const f32x4*)sp, s1 = *(const f32x4*)(sp + 4);
; #pragma unroll
;                 for (int j = 0; j < 8; ++j) { const float x1 = bf2f((bf16_t)a1[j]), x2 = bf2f((bf16_t)a2[j]); const float cc = j < 4 ? c0[j & 3] : c1[j & 3], sn = j < 4 ? s0[j & 3] : s1[j & 3];
;                     o1[j] = bf2f(f2bf(x1 * cc - x2 * sn)); o2[j] = bf2f(f2bf(x1 * sn + x2 * cc)); }
;                 u32x4 w1, w2;
;                 w1.x = pg8::cvt_pk_bf16(o1[0], o1[1]); w1.y = pg8::cvt_pk_bf16(o1[2], o1[3]); w1.z = pg8::cvt_pk_bf16(o1[4], o1[5]); w1.w = pg8::cvt_pk_bf16(o1[6], o1[7]);
;                 w2.x = pg8::cvt_pk_bf16(o2[0], o2[1]); w2.y = pg8::cvt_pk_bf16(o2[2], o2[3]); w2.z = pg8::cvt_pk_bf16(o2[4], o2[5]); w2.w = pg8::cvt_pk_bf16(o2[6], o2[7]);
;                 *(u32x4*)zp = w1; *(u32x4*)(zp + 32) = w2;
;             } else {
; #pragma unroll
;                 for (int j = 0; j < 8; ++j) { o1[j] = bf2f((bf16_t)a1[j]); o2[j] = bf2f((bf16_t)a2[j]); }
;             }
;             *(f32x4*)(Ks + r * 64 + 8 * pq) = (f32x4){o1[0], o1[1], o1[2], o1[3]}; *(f32x4*)(Ks + r * 64 + 8 * pq + 4) = (f32x4){o1[4], o1[5], o1[6], o1[7]};
;             *(f32x4*)(Ks + r * 64 + 32 + 8 * pq) = (f32x4){o2[0], o2[1], o2[2], o2[3]}; *(f32x4*)(Ks + r * 64 + 32 + 8 * pq + 4) = (f32x4){o2[4], o2[5], o2[6], o2[7]};
;         }
; #pragma unroll
;         for (int q = 0; q < 2; ++q) { const int idx = tid + 512 * q; const int r = idx >> 3, pc = idx & 7;
;             const bf16x8 vv = *(const bf16x8*)(Z + (size_t)(t0 + r) * INW + vc + 8 * pc);
;             *(f32x4*)(Vs + r * 64 + 8 * pc) = (f32x4){bf2f((bf16_t)vv[0]), bf2f((bf16_t)vv[1]), bf2f((bf16_t)vv[2]), bf2f((bf16_t)vv[3])};
.LBB0_866:
	s_or_b64 exec, exec, s[12:13]
	v_add_u32_e32 v12, s19, v36
	s_waitcnt vmcnt(0)
	v_mov_b64_e32 v[0:1], s[4:5]
	v_mad_i64_i32 v[0:1], s[12:13], v12, s54, v[0:1]
	s_lshl_b32 s80, s18, 7
	v_lshl_add_u64 v[0:1], v[0:1], 0, s[80:81]
	v_lshl_add_u64 v[30:31], v[0:1], 0, v[144:145]
	global_load_dwordx4 v[0:3], v[30:31], off offset:3584
	global_load_dwordx4 v[8:11], v[30:31], off offset:3648
	v_mov_b64_e32 v[60:61], s[4:5]
	v_lshl_add_u64 v[60:61], v[60:61], 0, s[80:81]
	v_mov_b32_e32 v76, 0x1000
	v_mov_b32_e32 v77, 0
	v_lshl_add_u64 v[60:61], v[60:61], 0, v[76:77]
	v_mov_b32_e32 v62, v28
	v_mov_b32_e32 v63, 0
	v_add_u32_e32 v64, s19, v38
	v_mad_i64_i32 v[64:65], s[12:13], v64, s54, v[60:61]
	v_lshl_add_u64 v[64:65], v[64:65], 0, v[62:63]
	v_add_u32_e32 v66, s19, v39
	v_mad_i64_i32 v[66:67], s[12:13], v66, s54, v[60:61]
	v_lshl_add_u64 v[66:67], v[66:67], 0, v[62:63]
	global_load_dwordx4 v[68:71], v[64:65], off offset:512
	global_load_dwordx4 v[72:75], v[66:67], off offset:512
	s_mov_b64 s[12:13], -1
	s_andn2_b64 vcc, exec, s[10:11]
	s_waitcnt lgkmcnt(0)
	s_waitcnt vmcnt(3)
	v_lshlrev_b32_sdwa v4, v204, v0 dst_sel:DWORD dst_unused:UNUSED_PAD src0_sel:DWORD src1_sel:WORD_0
	v_lshlrev_b32_sdwa v5, v204, v0 dst_sel:DWORD dst_unused:UNUSED_PAD src0_sel:DWORD src1_sel:WORD_1
	v_lshlrev_b32_sdwa v6, v204, v1 dst_sel:DWORD dst_unused:UNUSED_PAD src0_sel:DWORD src1_sel:WORD_0
	v_lshlrev_b32_sdwa v7, v204, v1 dst_sel:DWORD dst_unused:UNUSED_PAD src0_sel:DWORD src1_sel:WORD_1
	v_lshlrev_b32_sdwa v0, v204, v2 dst_sel:DWORD dst_unused:UNUSED_PAD src0_sel:DWORD src1_sel:WORD_0
	v_lshlrev_b32_sdwa v1, v204, v2 dst_sel:DWORD dst_unused:UNUSED_PAD src0_sel:DWORD src1_sel:WORD_1
	v_lshlrev_b32_sdwa v2, v204, v3 dst_sel:DWORD dst_unused:UNUSED_PAD src0_sel:DWORD src1_sel:WORD_0
	v_lshlrev_b32_sdwa v3, v204, v3 dst_sel:DWORD dst_unused:UNUSED_PAD src0_sel:DWORD src1_sel:WORD_1
	s_waitcnt vmcnt(2)
	v_lshlrev_b32_sdwa v20, v204, v8 dst_sel:DWORD dst_unused:UNUSED_PAD src0_sel:DWORD src1_sel:WORD_0
	v_lshlrev_b32_sdwa v21, v204, v8 dst_sel:DWORD dst_unused:UNUSED_PAD src0_sel:DWORD src1_sel:WORD_1
	v_lshlrev_b32_sdwa v22, v204, v9 dst_sel:DWORD dst_unused:UNUSED_PAD src0_sel:DWORD src1_sel:WORD_0
	v_lshlrev_b32_sdwa v23, v204, v9 dst_sel:DWORD dst_unused:UNUSED_PAD src0_sel:DWORD src1_sel:WORD_1
	v_lshlrev_b32_sdwa v8, v204, v10 dst_sel:DWORD dst_unused:UNUSED_PAD src0_sel:DWORD src1_sel:WORD_0
	v_lshlrev_b32_sdwa v9, v204, v10 dst_sel:DWORD dst_unused:UNUSED_PAD src0_sel:DWORD src1_sel:WORD_1
	v_lshlrev_b32_sdwa v10, v204, v11 dst_sel:DWORD dst_unused:UNUSED_PAD src0_sel:DWORD src1_sel:WORD_0
	v_lshlrev_b32_sdwa v11, v204, v11 dst_sel:DWORD dst_unused:UNUSED_PAD src0_sel:DWORD src1_sel:WORD_1
	s_waitcnt vmcnt(0)
	s_cbranch_vccnz .LBB0_868
	s_mov_b64 s[12:13], 0

; __device__ __forceinline__ float bf2f(bf16_t b) { return __uint_as_float(((unsigned)b) << 16); }
; __device__ __forceinline__ void m1_rope_states(const KQ p_in, int e, float* sm) {
;     ...
;             *(f32x4*)(Ks + r * 64 + 8 * pq) = (f32x4){o1[0], o1[1], o1[2], o1[3]}; *(f32x4*)(Ks + r * 64 + 8 * pq + 4) = (f32x4){o1[4], o1[5], o1[6], o1[7]};
;             *(f32x4*)(Ks + r * 64 + 32 + 8 * pq) = (f32x4){o2[0], o2[1], o2[2], o2[3]}; *(f32x4*)(Ks + r * 64 + 32 + 8 * pq + 4) = (f32x4){o2[4], o2[5], o2[6], o2[7]};
;         }
; #pragma unroll
;         for (int q = 0; q < 2; ++q) { const int idx = tid + 512 * q; const int r = idx >> 3, pc = idx & 7;
;             const bf16x8 vv = *(const bf16x8*)(Z + (size_t)(t0 + r) * INW + vc + 8 * pc);
;             *(f32x4*)(Vs + r * 64 + 8 * pc) = (f32x4){bf2f((bf16_t)vv[0]), bf2f((bf16_t)vv[1]), bf2f((bf16_t)vv[2]), bf2f((bf16_t)vv[3])};
;             *(f32x4*)(Vs + r * 64 + 8 * pc + 4) = (f32x4){bf2f((bf16_t)vv[4]), bf2f((bf16_t)vv[5]), bf2f((bf16_t)vv[6]), bf2f((bf16_t)vv[7])}; }
;         __syncthreads();
;         const int d = tid >> 3, e0 = (tid & 7) * 8;
;         float af[8], ab[8];
; #pragma unroll
;         for (int j = 0; j < 8; ++j) { af[j] = 0.f; ab[j] = 0.f; }
.LBB0_870:
	s_lshl_b32 s10, s18, 6
	s_lshl_b32 s10, s10, 1
	s_add_u32 s10, s4, s10
	s_addc_u32 s11, s5, 0
	ds_write_b128 v37, v[4:7]
	ds_write_b128 v37, v[0:3] offset:16
	ds_write_b128 v37, v[20:23] offset:128
	ds_write_b128 v37, v[8:11] offset:144
	v_add_u32_e32 v0, s19, v38
	v_mov_b64_e32 v[4:5], s[10:11]
	v_mad_i64_i32 v[0:1], s[10:11], v0, s54, v[4:5]
	v_mov_b32_e32 v29, v145
	v_lshl_add_u64 v[0:1], v[0:1], 0, v[28:29]
	s_movk_i32 s12, 0x1000
	v_add_co_u32_e32 v0, vcc, s12, v0
	v_add_u32_e32 v6, s19, v39
	s_nop 0
	v_addc_co_u32_e32 v1, vcc, 0, v1, vcc
	s_nop 0
	v_mad_i64_i32 v[4:5], s[10:11], v6, s54, v[4:5]
	v_lshl_add_u64 v[4:5], v[4:5], 0, v[28:29]
	v_add_co_u32_e32 v12, vcc, s12, v4
	s_mov_b32 s10, 0
	s_nop 0
	v_addc_co_u32_e32 v13, vcc, 0, v5, vcc
	v_mov_b32_e32 v16, v41
	v_mov_b32_e32 v17, v40
	s_waitcnt vmcnt(1) lgkmcnt(0)
	s_waitcnt vmcnt(0)
	v_and_b32_e32 v7, 0xffff0000, v69
	v_and_b32_e32 v5, 0xffff0000, v68
	v_lshlrev_b32_e32 v6, 16, v69
	v_lshlrev_b32_e32 v4, 16, v68
	v_and_b32_e32 v11, 0xffff0000, v71
	v_and_b32_e32 v9, 0xffff0000, v70
	v_lshlrev_b32_e32 v10, 16, v71
	v_lshlrev_b32_e32 v8, 16, v70
	ds_write_b128 v42, v[4:7] offset:32768
	ds_write_b128 v42, v[8:11] offset:32784
	s_nop 0
	v_mov_b32_e32 v6, 0
	v_mov_b32_e32 v7, v6
	v_mov_b32_e32 v12, v6
	v_mov_b32_e32 v13, v6
	v_mov_b32_e32 v14, v6
	v_mov_b32_e32 v15, v6
	v_mov_b32_e32 v4, v6
	v_mov_b32_e32 v5, v6
	v_mov_b32_e32 v2, v6
	v_mov_b32_e32 v3, v6
	v_mov_b32_e32 v8, v6
	v_mov_b32_e32 v9, v6
	v_mov_b32_e32 v10, v6
	v_mov_b32_e32 v11, v6
	v_mov_b32_e32 v0, v6
	v_mov_b32_e32 v1, v6
	s_waitcnt lgkmcnt(0)
	s_waitcnt vmcnt(0)
	v_and_b32_e32 v47, 0xffff0000, v73
	v_and_b32_e32 v45, 0xffff0000, v72
	v_lshlrev_b32_e32 v46, 16, v73
	v_lshlrev_b32_e32 v44, 16, v72
	v_and_b32_e32 v51, 0xffff0000, v75
	v_and_b32_e32 v49, 0xffff0000, v74
	v_lshlrev_b32_e32 v50, 16, v75
	v_lshlrev_b32_e32 v48, 16, v74
	ds_write_b128 v43, v[44:47] offset:32768
	ds_write_b128 v43, v[48:51] offset:32784
	s_waitcnt lgkmcnt(0)
	s_barrier

; __device__ __forceinline__ void row_exchange(const f32x4 (&v)[2][2][4][2], const Unit& u, int wr, int wc, int fr, int fq, LAS unsigned char* lds, int wid, int lane, float* slots, unsigned* cnt) {
;     ...
;         __builtin_amdgcn_fence(__ATOMIC_ACQUIRE, "agent");
;     }
;     asm volatile("s_waitcnt vmcnt(0) lgkmcnt(0)" ::: "memory"); __builtin_amdgcn_s_barrier(); asm volatile("" ::: "memory");
;     if (lane < 32) {
;         const unsigned* sl = (const unsigned*)slots + (size_t)(u.pm * BM + row) * 4;
;         float tot = 0.f;
; #pragma unroll
;         for (int t = 0; t < 4; ++t) tot += __uint_as_float(__hip_atomic_load(sl + t, __ATOMIC_RELAXED, __HIP_MEMORY_SCOPE_AGENT));
;         S[row] = tot;
;     }
.LBB0_1113:
	v_readlane_b32 s62, v252, 22
	s_nop 0
.LBB0_1114:
	s_waitcnt vmcnt(0) lgkmcnt(0)
	s_barrier
	s_lshl_b32 s50, s33, 8
	s_waitcnt lgkmcnt(0)
	v_add_u32_e32 v130, s50, v179
	v_ashrrev_i32_e32 v131, 31, v130
	s_and_saveexec_b64 s[48:49], s[4:5]
	s_cbranch_execz .LBB0_1116
	v_lshl_add_u64 v[128:129], v[130:131], 4, s[0:1]
	s_nop 0
	global_load_dword v132, v[128:129], off sc1
	global_load_dword v133, v[128:129], off offset:4 sc1
	global_load_dword v212, v[128:129], off offset:8 sc1
	global_load_dword v213, v[128:129], off offset:12 sc1
	v_lshl_add_u32 v129, v179, 2, 0
	s_waitcnt vmcnt(0) lgkmcnt(0)
	v_add_f32_e32 v132, 0, v132
	v_add_f32_e32 v132, v132, v133
	v_add_f32_e32 v132, v132, v212
	v_add_f32_e32 v128, v132, v213
	ds_write_b32 v129, v128 offset:4096

; __device__ __forceinline__ void row_exchange(const f32x4 (&v)[2][2][4][2], const Unit& u, int wr, int wc, int fr, int fq, LAS unsigned char* lds, int wid, int lane, float* slots, unsigned* cnt) {
;     ...
;         __builtin_amdgcn_fence(__ATOMIC_ACQUIRE, "agent");
;     }
;     asm volatile("s_waitcnt vmcnt(0) lgkmcnt(0)" ::: "memory"); __builtin_amdgcn_s_barrier(); asm volatile("" ::: "memory");
;     if (lane < 32) {
;         const unsigned* sl = (const unsigned*)slots + (size_t)(u.pm * BM + row) * 4;
;         float tot = 0.f;
; #pragma unroll
;         for (int t = 0; t < 4; ++t) tot += __uint_as_float(__hip_atomic_load(sl + t, __ATOMIC_RELAXED, __HIP_MEMORY_SCOPE_AGENT));
;         S[row] = tot;
;     }
.LBB0_1149:
	s_nop 0
.LBB0_1150:
	s_waitcnt vmcnt(0) lgkmcnt(0)
	s_barrier
	s_and_saveexec_b64 s[6:7], s[4:5]
	s_cbranch_execz .LBB0_1152
	v_lshl_add_u64 v[130:131], v[130:131], 4, s[0:1]
	s_nop 0
	global_load_dword v132, v[130:131], off sc1
	global_load_dword v133, v[130:131], off offset:4 sc1
	global_load_dword v212, v[130:131], off offset:8 sc1
	global_load_dword v213, v[130:131], off offset:12 sc1
	v_lshl_add_u32 v131, v179, 2, 0
	s_waitcnt vmcnt(0) lgkmcnt(0)
	v_add_f32_e32 v132, 0, v132
	v_add_f32_e32 v132, v132, v133
	v_add_f32_e32 v132, v132, v212
	v_add_f32_e32 v130, v132, v213
	ds_write_b32 v131, v130 offset:4096

; #define PG8_STAGE(bufoff, gbase, voff) do { _Pragma("unroll") for (int _i = 0; _i < 2; ++_i) \
;         __builtin_amdgcn_global_load_lds((const unsigned*)((const char*)(gbase) + (voff)[_i]), (LAS unsigned*)(lds + (bufoff) + ldsw + _i * 8192), 16, 0, 0); } while (0)
; #define PG8_LDA(dst, b, h) do { _Pragma("unroll") for (int m = 0; m < 4; ++m) _Pragma("unroll") for (int k = 0; k < 2; ++k) dst[m][k] = *(const LAS bf16x8*)(lds + PG8_SA(b, h) + aoff + m * 2048 + k * 1024); } while (0)
; #define PG8_LDB(dst, b, h) do { _Pragma("unroll") for (int n = 0; n < 2; ++n) _Pragma("unroll") for (int k = 0; k < 2; ++k) dst[n][k] = *(const LAS bf16x8*)(lds + PG8_SB(b, h) + boff + n * 2048 + k * 1024); } while (0)
; #define PG8_MMA(ai, bj, At, Bt) do { __builtin_amdgcn_s_setprio(1); _Pragma("unroll") for (int m = 0; m < 4; ++m) _Pragma("unroll") for (int n = 0; n < 2; ++n) _Pragma("unroll") for (int k = 0; k < 2; ++k) \
;         acc[ai][bj][m][n] = __builtin_amdgcn_mfma_f32_16x16x32_bf16(Bt[n][k], At[m][k], acc[ai][bj][m][n], 0, 0, 0); __builtin_amdgcn_s_setprio(0); } while (0)
; #define PG8_WAIT_L(n) asm volatile("s_waitcnt lgkmcnt(" #n ")" ::: "memory")
; #define PG8_BAR __builtin_amdgcn_s_barrier()
; #define PG8_SCHED __builtin_amdgcn_sched_barrier(0)
; template <class Epi, class Sched>
; __device__ __forceinline__ void gemm_phase(LAS unsigned char* lds, const Gemm g, const Sched& S, const Epi& E) {
;     ...
;             const char* a1 = cA + (size_t)(t + 1) * kstep;
;             const char* a2 = last ? nA : cA + (size_t)(t + 2) * kstep; const char* b2 = last ? nB : cB + (size_t)(t + 2) * kstep;
;             const char* a3 = a2 + kstep; const char* b3 = b2 + kstep;
;             PG8_LDB(B0, 0, 0); PG8_SCHED; PG8_LDA(At, 0, 0); PG8_STAGE(PG8_SA(1, 1), a1 + hstep, voffA);
;             PG8_WAIT_L(8); PG8_BAR; PG8_WAIT_L(0); PG8_MMA(0, 0, At, B0); PG8_BAR; PG8_SCHED;
;             PG8_LDB(B1, 0, 1); PG8_STAGE(PG8_SB(0, 0), b2, voffB);
;             PG8_BAR; PG8_WAIT_L(0); PG8_MMA(0, 1, At, B1); PG8_BAR;
;             PG8_LDA(At, 0, 1); PG8_STAGE(PG8_SA(0, 0), a2, voffA);
;             PG8_BAR; PG8_WAIT_L(0); PG8_MMA(1, 0, At, B0); PG8_BAR; PG8_SCHED;
.LBB0_1159:
	s_add_i32 s8, s26, 2
	s_mov_b32 s9, s81
	s_or_b32 s80, s26, 1
	s_lshl_b64 s[28:29], s[8:9], 7
	s_cmp_lg_u32 s26, s37
	s_cselect_b32 s18, s28, 0
	s_cselect_b32 s9, s29, 0
	s_add_u32 s26, s4, s18
	s_addc_u32 s27, s5, s9
	s_add_i32 s19, 0, 0x10000
	v_add_u32_e32 v142, s19, v132
	ds_read_b128 v[134:137], v142
	ds_read_b128 v[138:141], v142 offset:1024
	ds_read_b128 v[154:157], v142 offset:2048
	ds_read_b128 v[158:161], v142 offset:3072
	s_add_u32 s28, s0, s18
	s_addc_u32 s29, s1, s9
	s_lshl_b64 s[38:39], s[80:81], 7
	s_add_u32 s38, s6, s38
	s_addc_u32 s39, s7, s39
	v_lshl_add_u64 v[142:143], s[38:39], 0, v[144:145]
	s_add_i32 m0, s17, 0xc000
	ds_read_b128 v[162:165], v133
	ds_read_b128 v[166:169], v133 offset:1024
	ds_read_b128 v[170:173], v133 offset:2048
	ds_read_b128 v[174:177], v133 offset:3072
	ds_read_b128 v[178:181], v133 offset:4096
	ds_read_b128 v[182:185], v133 offset:5120
	ds_read_b128 v[208:211], v133 offset:6144
	ds_read_b128 v[212:215], v133 offset:7168
	global_load_lds_dwordx4 v[142:143], off
	v_lshl_add_u64 v[142:143], s[38:39], 0, v[128:129]
	s_add_i32 m0, s17, 0xe000
	s_nop 0
	global_load_lds_dwordx4 v[142:143], off
	s_waitcnt lgkmcnt(8)
	s_barrier
	s_waitcnt lgkmcnt(0)
	s_setprio 1
	v_mfma_f32_16x16x32_bf16 v[124:127], v[134:137], v[162:165], v[124:127]
	v_mfma_f32_16x16x32_bf16 v[120:123], v[154:157], v[162:165], v[120:123]
	v_mfma_f32_16x16x32_bf16 v[116:119], v[134:137], v[170:173], v[116:119]
	v_mfma_f32_16x16x32_bf16 v[112:115], v[154:157], v[170:173], v[112:115]
	v_mfma_f32_16x16x32_bf16 v[104:107], v[134:137], v[178:181], v[104:107]
	v_mfma_f32_16x16x32_bf16 v[96:99], v[154:157], v[178:181], v[96:99]
	v_mfma_f32_16x16x32_bf16 v[88:91], v[134:137], v[208:211], v[88:91]
	v_mfma_f32_16x16x32_bf16 v[80:83], v[154:157], v[208:211], v[80:83]
	v_mfma_f32_16x16x32_bf16 v[124:127], v[138:141], v[166:169], v[124:127]
	v_mfma_f32_16x16x32_bf16 v[120:123], v[158:161], v[166:169], v[120:123]
	v_mfma_f32_16x16x32_bf16 v[116:119], v[138:141], v[174:177], v[116:119]
	v_mfma_f32_16x16x32_bf16 v[112:115], v[158:161], v[174:177], v[112:115]
	v_mfma_f32_16x16x32_bf16 v[104:107], v[138:141], v[182:185], v[104:107]
	v_mfma_f32_16x16x32_bf16 v[96:99], v[158:161], v[182:185], v[96:99]
	v_mfma_f32_16x16x32_bf16 v[88:91], v[138:141], v[212:215], v[88:91]
	v_mfma_f32_16x16x32_bf16 v[80:83], v[158:161], v[212:215], v[80:83]
	s_setprio 0
	s_barrier
	s_add_i32 s9, 0, 0x14000
	v_add_u32_e32 v142, s9, v132
	s_add_i32 s18, s19, s2
	ds_read_b128 v[216:219], v142
	ds_read_b128 v[220:223], v142 offset:1024
	ds_read_b128 v[224:227], v142 offset:2048
	ds_read_b128 v[228:231], v142 offset:3072
	v_lshl_add_u64 v[142:143], s[28:29], 0, v[144:145]
	s_mov_b32 m0, s18
	v_lshl_add_u64 v[186:187], s[28:29], 0, v[128:129]
	global_load_lds_dwordx4 v[142:143], off
	s_add_i32 m0, s18, 0x2000
	s_nop 0
	global_load_lds_dwordx4 v[186:187], off
	s_barrier
	s_waitcnt lgkmcnt(0)
	s_setprio 1
	v_mfma_f32_16x16x32_bf16 v[108:111], v[216:219], v[162:165], v[108:111]
	v_mfma_f32_16x16x32_bf16 v[100:103], v[224:227], v[162:165], v[100:103]
	v_mfma_f32_16x16x32_bf16 v[92:95], v[216:219], v[170:173], v[92:95]
	v_mfma_f32_16x16x32_bf16 v[84:87], v[224:227], v[170:173], v[84:87]
	v_mfma_f32_16x16x32_bf16 v[76:79], v[216:219], v[178:181], v[76:79]
	v_mfma_f32_16x16x32_bf16 v[72:75], v[224:227], v[178:181], v[72:75]
	v_mfma_f32_16x16x32_bf16 v[68:71], v[216:219], v[208:211], v[68:71]
	v_mfma_f32_16x16x32_bf16 v[64:67], v[224:227], v[208:211], v[64:67]
	v_mfma_f32_16x16x32_bf16 v[108:111], v[220:223], v[166:169], v[108:111]
	v_mfma_f32_16x16x32_bf16 v[100:103], v[228:231], v[166:169], v[100:103]
	v_mfma_f32_16x16x32_bf16 v[92:95], v[220:223], v[174:177], v[92:95]
	v_mfma_f32_16x16x32_bf16 v[84:87], v[228:231], v[174:177], v[84:87]
	v_mfma_f32_16x16x32_bf16 v[76:79], v[220:223], v[182:185], v[76:79]
	v_mfma_f32_16x16x32_bf16 v[72:75], v[228:231], v[182:185], v[72:75]
	v_mfma_f32_16x16x32_bf16 v[68:71], v[220:223], v[212:215], v[68:71]
	v_mfma_f32_16x16x32_bf16 v[64:67], v[228:231], v[212:215], v[64:67]
	s_setprio 0
	s_mov_b32 m0, s17
	v_lshl_add_u64 v[192:193], s[26:27], 0, v[144:145]
	s_barrier
	ds_read_b128 v[162:165], v133 offset:16384
	ds_read_b128 v[166:169], v133 offset:17408
	ds_read_b128 v[170:173], v133 offset:18432
	ds_read_b128 v[174:177], v133 offset:19456
	ds_read_b128 v[178:181], v133 offset:20480
	ds_read_b128 v[182:185], v133 offset:21504
	ds_read_b128 v[208:211], v133 offset:22528
	ds_read_b128 v[212:215], v133 offset:23552
	global_load_lds_dwordx4 v[192:193], off
	v_lshl_add_u64 v[232:233], s[26:27], 0, v[128:129]
	s_mov_b32 m0, s30
	s_nop 0
	global_load_lds_dwordx4 v[232:233], off
	s_barrier
	s_waitcnt lgkmcnt(0)
	s_setprio 1
	v_mfma_f32_16x16x32_bf16 v[60:63], v[134:137], v[162:165], v[60:63]
	v_mfma_f32_16x16x32_bf16 v[56:59], v[154:157], v[162:165], v[56:59]
	v_mfma_f32_16x16x32_bf16 v[52:55], v[134:137], v[170:173], v[52:55]
	v_mfma_f32_16x16x32_bf16 v[48:51], v[154:157], v[170:173], v[48:51]
	v_mfma_f32_16x16x32_bf16 v[40:43], v[134:137], v[178:181], v[40:43]
	v_mfma_f32_16x16x32_bf16 v[32:35], v[154:157], v[178:181], v[32:35]
	v_mfma_f32_16x16x32_bf16 v[24:27], v[134:137], v[208:211], v[24:27]
	v_mfma_f32_16x16x32_bf16 v[16:19], v[154:157], v[208:211], v[16:19]
	v_mfma_f32_16x16x32_bf16 v[60:63], v[138:141], v[166:169], v[60:63]
	v_mfma_f32_16x16x32_bf16 v[56:59], v[158:161], v[166:169], v[56:59]
	v_mfma_f32_16x16x32_bf16 v[52:55], v[138:141], v[174:177], v[52:55]
	v_mfma_f32_16x16x32_bf16 v[48:51], v[158:161], v[174:177], v[48:51]
	v_mfma_f32_16x16x32_bf16 v[40:43], v[138:141], v[182:185], v[40:43]
	v_mfma_f32_16x16x32_bf16 v[32:35], v[158:161], v[182:185], v[32:35]
	v_mfma_f32_16x16x32_bf16 v[24:27], v[138:141], v[212:215], v[24:27]
	v_mfma_f32_16x16x32_bf16 v[16:19], v[158:161], v[212:215], v[16:19]
	s_setprio 0
	s_barrier
; #define PG8_STAGE(bufoff, gbase, voff) do { _Pragma("unroll") for (int _i = 0; _i < 2; ++_i) \
;         __builtin_amdgcn_global_load_lds((const unsigned*)((const char*)(gbase) + (voff)[_i]), (LAS unsigned*)(lds + (bufoff) + ldsw + _i * 8192), 16, 0, 0); } while (0)
; #define PG8_LDA(dst, b, h) do { _Pragma("unroll") for (int m = 0; m < 4; ++m) _Pragma("unroll") for (int k = 0; k < 2; ++k) dst[m][k] = *(const LAS bf16x8*)(lds + PG8_SA(b, h) + aoff + m * 2048 + k * 1024); } while (0)
; #define PG8_LDB(dst, b, h) do { _Pragma("unroll") for (int n = 0; n < 2; ++n) _Pragma("unroll") for (int k = 0; k < 2; ++k) dst[n][k] = *(const LAS bf16x8*)(lds + PG8_SB(b, h) + boff + n * 2048 + k * 1024); } while (0)
; #define PG8_MMA(ai, bj, At, Bt) do { __builtin_amdgcn_s_setprio(1); _Pragma("unroll") for (int m = 0; m < 4; ++m) _Pragma("unroll") for (int n = 0; n < 2; ++n) _Pragma("unroll") for (int k = 0; k < 2; ++k) \
;         acc[ai][bj][m][n] = __builtin_amdgcn_mfma_f32_16x16x32_bf16(Bt[n][k], At[m][k], acc[ai][bj][m][n], 0, 0, 0); __builtin_amdgcn_s_setprio(0); } while (0)
; #define PG8_WAIT_V(n) asm volatile("s_waitcnt vmcnt(" #n ")" ::: "memory")
; #define PG8_WAIT_L(n) asm volatile("s_waitcnt lgkmcnt(" #n ")" ::: "memory")
; #define PG8_BAR __builtin_amdgcn_s_barrier()
; #define PG8_SCHED __builtin_amdgcn_sched_barrier(0)
; template <class Epi, class Sched>
; __device__ __forceinline__ void gemm_phase(LAS unsigned char* lds, const Gemm g, const Sched& S, const Epi& E) {
;     ...
;             PG8_STAGE(PG8_SB(0, 1), b2 + hstep, voffB);
;             PG8_WAIT_V(6); PG8_BAR; PG8_MMA(1, 1, At, B1); PG8_BAR;
;             PG8_LDB(B0, 1, 0); PG8_SCHED; PG8_LDA(At, 1, 0); PG8_STAGE(PG8_SA(0, 1), a2 + hstep, voffA);
;             PG8_WAIT_L(8); PG8_BAR; PG8_WAIT_L(0); PG8_MMA(0, 0, At, B0); PG8_BAR; PG8_SCHED;
;             PG8_LDB(B1, 1, 1); PG8_STAGE(PG8_SB(1, 0), b3, voffB);
;             PG8_BAR; PG8_WAIT_L(0); PG8_MMA(0, 1, At, B1); PG8_BAR;
;             PG8_LDA(At, 1, 1); PG8_STAGE(PG8_SA(1, 0), a3, voffA);
;             PG8_BAR; PG8_WAIT_L(0); PG8_MMA(1, 0, At, B0); PG8_BAR; PG8_SCHED;
	s_add_u32 s28, s28, s13
	s_addc_u32 s29, s29, 0
	s_add_i32 s9, s9, s2
	v_lshl_add_u64 v[234:235], s[28:29], 0, v[144:145]
	s_mov_b32 m0, s9
	v_lshl_add_u64 v[236:237], s[28:29], 0, v[128:129]
	global_load_lds_dwordx4 v[234:235], off
	s_add_i32 m0, s9, 0x2000
	s_nop 0
	global_load_lds_dwordx4 v[236:237], off
	s_waitcnt vmcnt(6)
	s_barrier
	s_setprio 1
	v_mfma_f32_16x16x32_bf16 v[44:47], v[216:219], v[162:165], v[44:47]
	v_mfma_f32_16x16x32_bf16 v[36:39], v[224:227], v[162:165], v[36:39]
	v_mfma_f32_16x16x32_bf16 v[28:31], v[216:219], v[170:173], v[28:31]
	v_mfma_f32_16x16x32_bf16 v[20:23], v[224:227], v[170:173], v[20:23]
	v_mfma_f32_16x16x32_bf16 v[12:15], v[216:219], v[178:181], v[12:15]
	v_mfma_f32_16x16x32_bf16 v[8:11], v[224:227], v[178:181], v[8:11]
	v_mfma_f32_16x16x32_bf16 v[4:7], v[216:219], v[208:211], v[4:7]
	v_mfma_f32_16x16x32_bf16 v[0:3], v[224:227], v[208:211], v[0:3]
	v_mfma_f32_16x16x32_bf16 v[44:47], v[220:223], v[166:169], v[44:47]
	v_mfma_f32_16x16x32_bf16 v[36:39], v[228:231], v[166:169], v[36:39]
	v_mfma_f32_16x16x32_bf16 v[28:31], v[220:223], v[174:177], v[28:31]
	v_mfma_f32_16x16x32_bf16 v[20:23], v[228:231], v[174:177], v[20:23]
	v_mfma_f32_16x16x32_bf16 v[12:15], v[220:223], v[182:185], v[12:15]
	v_mfma_f32_16x16x32_bf16 v[8:11], v[228:231], v[182:185], v[8:11]
	v_mfma_f32_16x16x32_bf16 v[4:7], v[220:223], v[212:215], v[4:7]
	v_mfma_f32_16x16x32_bf16 v[0:3], v[228:231], v[212:215], v[0:3]
	s_setprio 0
	s_add_i32 s9, 0, 0x18000
	v_add_u32_e32 v158, s9, v132
	s_barrier
	ds_read_b128 v[134:137], v158
	ds_read_b128 v[138:141], v158 offset:1024
	ds_read_b128 v[154:157], v158 offset:2048
	ds_read_b128 v[158:161], v158 offset:3072
	s_add_u32 s26, s26, s13
	s_addc_u32 s27, s27, 0
	s_mov_b32 m0, s31
	v_lshl_add_u64 v[216:217], s[26:27], 0, v[144:145]
	ds_read_b128 v[162:165], v133 offset:32768
	ds_read_b128 v[166:169], v133 offset:33792
	ds_read_b128 v[170:173], v133 offset:34816
	ds_read_b128 v[174:177], v133 offset:35840
	ds_read_b128 v[178:181], v133 offset:36864
	ds_read_b128 v[182:185], v133 offset:37888
	ds_read_b128 v[208:211], v133 offset:38912
	ds_read_b128 v[212:215], v133 offset:39936
	global_load_lds_dwordx4 v[216:217], off
	v_lshl_add_u64 v[216:217], s[26:27], 0, v[128:129]
	s_mov_b32 m0, s33
	s_nop 0
	global_load_lds_dwordx4 v[216:217], off
	s_waitcnt lgkmcnt(8)
	s_barrier
	s_waitcnt lgkmcnt(0)
	s_setprio 1
	v_mfma_f32_16x16x32_bf16 v[124:127], v[134:137], v[162:165], v[124:127]
	v_mfma_f32_16x16x32_bf16 v[120:123], v[154:157], v[162:165], v[120:123]
	v_mfma_f32_16x16x32_bf16 v[116:119], v[134:137], v[170:173], v[116:119]
	v_mfma_f32_16x16x32_bf16 v[112:115], v[154:157], v[170:173], v[112:115]
	v_mfma_f32_16x16x32_bf16 v[104:107], v[134:137], v[178:181], v[104:107]
	v_mfma_f32_16x16x32_bf16 v[96:99], v[154:157], v[178:181], v[96:99]
	v_mfma_f32_16x16x32_bf16 v[88:91], v[134:137], v[208:211], v[88:91]
	v_mfma_f32_16x16x32_bf16 v[80:83], v[154:157], v[208:211], v[80:83]
	v_mfma_f32_16x16x32_bf16 v[124:127], v[138:141], v[166:169], v[124:127]
	v_mfma_f32_16x16x32_bf16 v[120:123], v[158:161], v[166:169], v[120:123]
	v_mfma_f32_16x16x32_bf16 v[116:119], v[138:141], v[174:177], v[116:119]
	v_mfma_f32_16x16x32_bf16 v[112:115], v[158:161], v[174:177], v[112:115]
	v_mfma_f32_16x16x32_bf16 v[104:107], v[138:141], v[182:185], v[104:107]
	v_mfma_f32_16x16x32_bf16 v[96:99], v[158:161], v[182:185], v[96:99]
	v_mfma_f32_16x16x32_bf16 v[88:91], v[138:141], v[212:215], v[88:91]
	v_mfma_f32_16x16x32_bf16 v[80:83], v[158:161], v[212:215], v[80:83]
	s_setprio 0
	s_barrier
	s_add_i32 s18, 0, 0x1c000
	s_add_i32 s9, s9, s2
	v_add_u32_e32 v228, s18, v132
	v_lshl_add_u64 v[142:143], v[142:143], 0, s[82:83]
	s_mov_b32 m0, s9
	ds_read_b128 v[216:219], v228
	ds_read_b128 v[220:223], v228 offset:1024
	ds_read_b128 v[224:227], v228 offset:2048
	ds_read_b128 v[228:231], v228 offset:3072
	global_load_lds_dwordx4 v[142:143], off
	v_lshl_add_u64 v[142:143], v[186:187], 0, s[82:83]
	s_add_i32 m0, s9, 0x2000
	s_nop 0
	global_load_lds_dwordx4 v[142:143], off
	s_barrier
	s_waitcnt lgkmcnt(0)
	s_setprio 1
	v_mfma_f32_16x16x32_bf16 v[108:111], v[216:219], v[162:165], v[108:111]
	v_mfma_f32_16x16x32_bf16 v[100:103], v[224:227], v[162:165], v[100:103]
	v_mfma_f32_16x16x32_bf16 v[92:95], v[216:219], v[170:173], v[92:95]
	v_mfma_f32_16x16x32_bf16 v[84:87], v[224:227], v[170:173], v[84:87]
	v_mfma_f32_16x16x32_bf16 v[76:79], v[216:219], v[178:181], v[76:79]
	v_mfma_f32_16x16x32_bf16 v[72:75], v[224:227], v[178:181], v[72:75]
	v_mfma_f32_16x16x32_bf16 v[68:71], v[216:219], v[208:211], v[68:71]
	v_mfma_f32_16x16x32_bf16 v[64:67], v[224:227], v[208:211], v[64:67]
	v_mfma_f32_16x16x32_bf16 v[108:111], v[220:223], v[166:169], v[108:111]
	v_mfma_f32_16x16x32_bf16 v[100:103], v[228:231], v[166:169], v[100:103]
	v_mfma_f32_16x16x32_bf16 v[92:95], v[220:223], v[174:177], v[92:95]
	v_mfma_f32_16x16x32_bf16 v[84:87], v[228:231], v[174:177], v[84:87]
	v_mfma_f32_16x16x32_bf16 v[76:79], v[220:223], v[182:185], v[76:79]
	v_mfma_f32_16x16x32_bf16 v[72:75], v[228:231], v[182:185], v[72:75]
	v_mfma_f32_16x16x32_bf16 v[68:71], v[220:223], v[212:215], v[68:71]
	v_mfma_f32_16x16x32_bf16 v[64:67], v[228:231], v[212:215], v[64:67]
	s_setprio 0
	s_mov_b32 m0, s35
	v_lshl_add_u64 v[142:143], v[192:193], 0, s[82:83]
	s_barrier
	ds_read_b128 v[162:165], v133 offset:49152
	ds_read_b128 v[166:169], v133 offset:50176
	ds_read_b128 v[170:173], v133 offset:51200
	ds_read_b128 v[174:177], v133 offset:52224
	ds_read_b128 v[178:181], v133 offset:53248
	ds_read_b128 v[182:185], v133 offset:54272
	ds_read_b128 v[208:211], v133 offset:55296
	ds_read_b128 v[212:215], v133 offset:56320
	global_load_lds_dwordx4 v[142:143], off
	v_lshl_add_u64 v[142:143], v[232:233], 0, s[82:83]
	s_mov_b32 m0, s36
	s_nop 0
	global_load_lds_dwordx4 v[142:143], off
	s_barrier
; #define PG8_STAGE(bufoff, gbase, voff) do { _Pragma("unroll") for (int _i = 0; _i < 2; ++_i) \
;         __builtin_amdgcn_global_load_lds((const unsigned*)((const char*)(gbase) + (voff)[_i]), (LAS unsigned*)(lds + (bufoff) + ldsw + _i * 8192), 16, 0, 0); } while (0)
; #define PG8_MMA(ai, bj, At, Bt) do { __builtin_amdgcn_s_setprio(1); _Pragma("unroll") for (int m = 0; m < 4; ++m) _Pragma("unroll") for (int n = 0; n < 2; ++n) _Pragma("unroll") for (int k = 0; k < 2; ++k) \
;         acc[ai][bj][m][n] = __builtin_amdgcn_mfma_f32_16x16x32_bf16(Bt[n][k], At[m][k], acc[ai][bj][m][n], 0, 0, 0); __builtin_amdgcn_s_setprio(0); } while (0)
; #define PG8_WAIT_V(n) asm volatile("s_waitcnt vmcnt(" #n ")" ::: "memory")
; #define PG8_WAIT_L(n) asm volatile("s_waitcnt lgkmcnt(" #n ")" ::: "memory")
; #define PG8_BAR __builtin_amdgcn_s_barrier()
; #define PG8_SCHED __builtin_amdgcn_sched_barrier(0)
;     __device__ __forceinline__ void operator()(const f32x4 (&acc)[2][2][4][2], const Unit& u, int wr, int wc, int fr, int fq) const {
;         const int row0 = u.pm * BM + wr * 64 + fr, col0 = u.pn * BM + wc * 32 + 4 * fq;
; #pragma unroll
;         for (int ai = 0; ai < 2; ++ai)
; #pragma unroll
;             for (int m = 0; m < 4; ++m) { float* rowp = C + (size_t)(row0 + ai * HALF + m * 16) * ldc + col0;
; #pragma unroll
;                 for (int bj = 0; bj < 2; ++bj)
; #pragma unroll
;                     for (int n = 0; n < 2; ++n) *(f32x4*)(rowp + bj * HALF + n * 16) = acc[ai][bj][m][n]; }
; template <class Epi, class Sched>
; __device__ __forceinline__ void gemm_phase(LAS unsigned char* lds, const Gemm g, const Sched& S, const Epi& E) {
;     ...
;             PG8_BAR; PG8_WAIT_L(0); PG8_MMA(1, 0, At, B0); PG8_BAR; PG8_SCHED;
;             PG8_STAGE(PG8_SB(1, 1), b3 + hstep, voffB);
;             PG8_WAIT_V(6); PG8_BAR; PG8_MMA(1, 1, At, B1); PG8_BAR;
	s_waitcnt lgkmcnt(0)
	s_setprio 1
	v_mfma_f32_16x16x32_bf16 v[60:63], v[134:137], v[162:165], v[60:63]
	v_mfma_f32_16x16x32_bf16 v[56:59], v[154:157], v[162:165], v[56:59]
	v_mfma_f32_16x16x32_bf16 v[52:55], v[134:137], v[170:173], v[52:55]
	v_mfma_f32_16x16x32_bf16 v[48:51], v[154:157], v[170:173], v[48:51]
	v_mfma_f32_16x16x32_bf16 v[40:43], v[134:137], v[178:181], v[40:43]
	v_mfma_f32_16x16x32_bf16 v[32:35], v[154:157], v[178:181], v[32:35]
	v_mfma_f32_16x16x32_bf16 v[24:27], v[134:137], v[208:211], v[24:27]
	v_mfma_f32_16x16x32_bf16 v[16:19], v[154:157], v[208:211], v[16:19]
	v_mfma_f32_16x16x32_bf16 v[60:63], v[138:141], v[166:169], v[60:63]
	v_mfma_f32_16x16x32_bf16 v[56:59], v[158:161], v[166:169], v[56:59]
	v_mfma_f32_16x16x32_bf16 v[52:55], v[138:141], v[174:177], v[52:55]
	v_mfma_f32_16x16x32_bf16 v[48:51], v[158:161], v[174:177], v[48:51]
	v_mfma_f32_16x16x32_bf16 v[40:43], v[138:141], v[182:185], v[40:43]
	v_mfma_f32_16x16x32_bf16 v[32:35], v[158:161], v[182:185], v[32:35]
	v_mfma_f32_16x16x32_bf16 v[24:27], v[138:141], v[212:215], v[24:27]
	v_mfma_f32_16x16x32_bf16 v[16:19], v[158:161], v[212:215], v[16:19]
	s_setprio 0
	s_barrier
	s_add_i32 s9, s18, s2
	v_lshl_add_u64 v[134:135], v[234:235], 0, s[82:83]
	s_mov_b32 m0, s9
	s_nop 0
	global_load_lds_dwordx4 v[134:135], off
	v_lshl_add_u64 v[134:135], v[236:237], 0, s[82:83]
	s_add_i32 m0, s9, 0x2000
	s_nop 0
	global_load_lds_dwordx4 v[134:135], off
	s_waitcnt vmcnt(6)
	s_barrier
	s_setprio 1
	v_mfma_f32_16x16x32_bf16 v[44:47], v[216:219], v[162:165], v[44:47]
	v_mfma_f32_16x16x32_bf16 v[36:39], v[224:227], v[162:165], v[36:39]
	v_mfma_f32_16x16x32_bf16 v[28:31], v[216:219], v[170:173], v[28:31]
	v_mfma_f32_16x16x32_bf16 v[20:23], v[224:227], v[170:173], v[20:23]
	v_mfma_f32_16x16x32_bf16 v[12:15], v[216:219], v[178:181], v[12:15]
	v_mfma_f32_16x16x32_bf16 v[8:11], v[224:227], v[178:181], v[8:11]
	v_mfma_f32_16x16x32_bf16 v[4:7], v[216:219], v[208:211], v[4:7]
	v_mfma_f32_16x16x32_bf16 v[0:3], v[224:227], v[208:211], v[0:3]
	v_mfma_f32_16x16x32_bf16 v[44:47], v[220:223], v[166:169], v[44:47]
	v_mfma_f32_16x16x32_bf16 v[36:39], v[228:231], v[166:169], v[36:39]
	v_mfma_f32_16x16x32_bf16 v[28:31], v[220:223], v[174:177], v[28:31]
	v_mfma_f32_16x16x32_bf16 v[20:23], v[228:231], v[174:177], v[20:23]
	v_mfma_f32_16x16x32_bf16 v[12:15], v[220:223], v[182:185], v[12:15]
	v_mfma_f32_16x16x32_bf16 v[8:11], v[228:231], v[182:185], v[8:11]
	v_mfma_f32_16x16x32_bf16 v[4:7], v[220:223], v[212:215], v[4:7]
	v_mfma_f32_16x16x32_bf16 v[0:3], v[228:231], v[212:215], v[0:3]
	s_setprio 0
	s_cmp_ge_u32 s8, s23
	s_mov_b32 s26, s8
	s_barrier
	s_cbranch_scc0 .LBB0_1159
	v_readlane_b32 s0, v251, 44
	v_readlane_b32 s4, v253, 49
	v_readlane_b32 s2, v251, 46
	v_readlane_b32 s5, v253, 50
	s_add_u32 s0, s4, s0
	v_add_u32_e32 v128, s2, v131
	v_readlane_b32 s2, v251, 48
	s_addc_u32 s1, s5, 0
	s_add_u32 s0, s0, 0x21fb4000
	v_lshl_or_b32 v129, v130, 2, s2
	v_or_b32_e32 v132, s34, v129
	v_ashrrev_i32_e32 v129, 31, v128
	s_addc_u32 s1, s1, 0
	v_lshlrev_b64 v[130:131], 12, v[128:129]
	v_lshl_add_u64 v[130:131], s[0:1], 0, v[130:131]
	v_lshlrev_b32_e32 v144, 2, v132
	v_lshl_add_u64 v[130:131], v[130:131], 0, v[144:145]
	global_store_dwordx4 v[130:131], v[124:127], off sc1
	global_store_dwordx4 v[130:131], v[120:123], off offset:64 sc1
	global_store_dwordx4 v[130:131], v[108:111], off offset:512 sc1
	global_store_dwordx4 v[130:131], v[100:103], off offset:576 sc1
	s_cmpk_lt_u32 s15, 0x100
	s_nop 0
	v_or_b32_e32 v100, 16, v128
	v_ashrrev_i32_e32 v101, 31, v100
	v_lshlrev_b64 v[100:101], 12, v[100:101]
	v_lshl_add_u64 v[100:101], s[0:1], 0, v[100:101]
	v_lshl_add_u64 v[100:101], v[100:101], 0, v[144:145]
	global_store_dwordx4 v[100:101], v[116:119], off sc1
	global_store_dwordx4 v[100:101], v[112:115], off offset:64 sc1
	global_store_dwordx4 v[100:101], v[92:95], off offset:512 sc1
	global_store_dwordx4 v[100:101], v[84:87], off offset:576 sc1
	s_nop 1
	v_or_b32_e32 v84, 32, v128
	v_ashrrev_i32_e32 v85, 31, v84
	v_lshlrev_b64 v[84:85], 12, v[84:85]
	v_lshl_add_u64 v[84:85], s[0:1], 0, v[84:85]
	v_lshl_add_u64 v[84:85], v[84:85], 0, v[144:145]
	global_store_dwordx4 v[84:85], v[104:107], off sc1
	global_store_dwordx4 v[84:85], v[96:99], off offset:64 sc1
	global_store_dwordx4 v[84:85], v[76:79], off offset:512 sc1
	global_store_dwordx4 v[84:85], v[72:75], off offset:576 sc1
	s_nop 1
	v_or_b32_e32 v72, 48, v128
	v_ashrrev_i32_e32 v73, 31, v72
	v_lshlrev_b64 v[72:73], 12, v[72:73]
	v_lshl_add_u64 v[72:73], s[0:1], 0, v[72:73]
	v_lshl_add_u64 v[72:73], v[72:73], 0, v[144:145]
	global_store_dwordx4 v[72:73], v[88:91], off sc1
	global_store_dwordx4 v[72:73], v[80:83], off offset:64 sc1
	global_store_dwordx4 v[72:73], v[68:71], off offset:512 sc1
	global_store_dwordx4 v[72:73], v[64:67], off offset:576 sc1
	s_mov_b64 s[0:1], 0x80000
	s_nop 0
	v_add_co_u32_e32 v66, vcc, s20, v130
	v_lshl_add_u64 v[64:65], v[130:131], 0, s[0:1]
	s_nop 0
	v_addc_co_u32_e32 v67, vcc, 0, v131, vcc
	s_mov_b64 s[0:1], 0x90000
	global_store_dwordx4 v[66:67], v[60:63], off sc1
	global_store_dwordx4 v[64:65], v[56:59], off offset:64 sc1
	global_store_dwordx4 v[64:65], v[44:47], off offset:512 sc1
	global_store_dwordx4 v[64:65], v[36:39], off offset:576 sc1
	s_nop 1
	v_lshl_add_u64 v[36:37], v[130:131], 0, s[0:1]
	s_mov_b32 s0, 0x90000
	v_add_co_u32_e32 v38, vcc, s0, v130
	s_mov_b64 s[0:1], 0xa0000
	s_nop 0
	v_addc_co_u32_e32 v39, vcc, 0, v131, vcc
	global_store_dwordx4 v[38:39], v[52:55], off sc1
	global_store_dwordx4 v[36:37], v[48:51], off offset:64 sc1
	global_store_dwordx4 v[36:37], v[28:31], off offset:512 sc1
	global_store_dwordx4 v[36:37], v[20:23], off offset:576 sc1
	s_nop 1
	v_add_co_u32_e32 v22, vcc, s21, v130
	v_lshl_add_u64 v[20:21], v[130:131], 0, s[0:1]
	s_nop 0
	v_addc_co_u32_e32 v23, vcc, 0, v131, vcc
	global_store_dwordx4 v[22:23], v[40:43], off sc1
	global_store_dwordx4 v[20:21], v[32:35], off offset:64 sc1
	global_store_dwordx4 v[20:21], v[12:15], off offset:512 sc1
	global_store_dwordx4 v[20:21], v[8:11], off offset:576 sc1
	s_mov_b64 s[0:1], 0xb0000
	s_nop 0
	v_add_co_u32_e32 v10, vcc, 0xb0000, v130
	v_lshl_add_u64 v[8:9], v[130:131], 0, s[0:1]
	s_nop 0
	v_addc_co_u32_e32 v11, vcc, 0, v131, vcc
	global_store_dwordx4 v[10:11], v[24:27], off sc1
	global_store_dwordx4 v[8:9], v[16:19], off offset:64 sc1
	global_store_dwordx4 v[8:9], v[4:7], off offset:512 sc1
	global_store_dwordx4 v[8:9], v[0:3], off offset:576 sc1
	s_waitcnt vmcnt(0)
	s_cbranch_scc0 .LBB0_1162
	s_barrier
